# v053_attnorder_q8
# baseline (speedup 1.0000x reference)
; __device__ __forceinline__ void attn_wave_item(const Params& p, int witem, const int tidx) {
;     ...
;     u32x4 vf[8], kn[8];
;     {
;       const int tn = tile > 0 ? tile - 1 : 0;
;       const char* vp = vbase + (size_t)tile * 8192;
;       const char* kp = kbase + (size_t)tn * 8192;
; #pragma unroll
;       for (int i = 0; i < 8; ++i) vf[i] = *reinterpret_cast<const u32x4*>(vp + i * 1024);
; #pragma unroll
;       for (int ks = 0; ks < 8; ++ks) kn[ks] = *reinterpret_cast<const u32x4*>(kp + ks * 1024);
;     }
;     __builtin_amdgcn_sched_barrier(0);
;     f32x16 S, S2;
; #pragma unroll
;     for (int i = 0; i < 16; ++i) { S[i] = 0.f; S2[i] = 0.f; }
; #pragma unroll
;     for (int ks = 0; ks < 8; ks += 2) {
;       u32x4 qa = *reinterpret_cast<const u32x4*>(qlds + ks * 1024);
;       u32x4 qb = *reinterpret_cast<const u32x4*>(qlds + (ks + 1) * 1024);
;       S = __builtin_amdgcn_mfma_f32_32x32x16_bf16(as_bf16x8(kf[ks]), as_bf16x8(qa), S, 0, 0, 0);
;       S2 = __builtin_amdgcn_mfma_f32_32x32x16_bf16(as_bf16x8(kf[ks + 1]), as_bf16x8(qb), S2, 0, 0, 0);
;     }
; #pragma unroll
;     for (int i = 0; i < 16; ++i) S[i] += S2[i];
;     const bool diag = (tile == qt);
;     float be[16], om[16];
; #pragma unroll
;     for (int r = 0; r < 16; ++r) {
;       float z = S[r];
;       float e = __builtin_amdgcn_exp2f(-fabsf(z));
;       float rr = __builtin_amdgcn_rcpf(1.f + e);
;       float sm = e * rr;
;       int kl = (r & 3) + 8 * (r >> 2) + 4 * half;
;       bool v = !diag || (kl < n);
;       bool pos = z >= 0.f;
;       be[r] = v ? (pos ? rr : sm) : 0.f;
;       om[r] = v ? (pos ? sm : rr) : 1.f;
;     }
.LBB0_119:
	ds_read_b128 v[226:229], v173
	ds_read_b128 v[84:87], v173 offset:1024
	ds_read_b128 v[204:207], v173 offset:2048
	ds_read_b128 v[222:225], v173 offset:3072
	ds_read_b128 v[230:233], v173 offset:4096
	ds_read_b128 v[234:237], v173 offset:5120
	ds_read_b128 v[238:241], v173 offset:6144
	ds_read_b128 v[242:245], v173 offset:7168
	v_sub_u32_e64 v162, v169, 1 clamp
	s_waitcnt vmcnt(0)
	v_mov_b64_e32 v[198:199], v[112:113]
	v_mov_b64_e32 v[202:203], v[108:109]
	v_mov_b64_e32 v[80:81], v[102:103]
	v_mov_b64_e32 v[64:65], v[98:99]
	v_mov_b64_e32 v[196:197], v[110:111]
	v_mov_b64_e32 v[200:201], v[106:107]
	v_mov_b64_e32 v[82:83], v[104:105]
	v_mov_b64_e32 v[66:67], v[100:101]
	v_mov_b64_e32 v[182:183], v[128:129]
	v_mov_b64_e32 v[186:187], v[124:125]
	v_mov_b64_e32 v[190:191], v[120:121]
	v_mov_b64_e32 v[194:195], v[116:117]
	v_mov_b64_e32 v[180:181], v[126:127]
	v_mov_b64_e32 v[184:185], v[122:123]
	v_mov_b64_e32 v[188:189], v[118:119]
	v_mov_b64_e32 v[192:193], v[114:115]
	s_cmp_lg_u32 s48, 0
	s_cselect_b64 s[50:51], -1, 0
	s_waitcnt lgkmcnt(7)
	s_setprio 1
	v_mfma_f32_32x32x16_bf16 v[64:79], v[64:67], v[226:229], 0
	s_or_b64 s[44:45], s[6:7], s[50:51]
	s_waitcnt lgkmcnt(6)
	v_mfma_f32_32x32x16_bf16 v[80:95], v[80:83], v[84:87], 0
	s_waitcnt lgkmcnt(5)
	v_mfma_f32_32x32x16_bf16 v[64:79], v[200:203], v[204:207], v[64:79]
	s_waitcnt lgkmcnt(4)
	v_mfma_f32_32x32x16_bf16 v[80:95], v[196:199], v[222:225], v[80:95]
	s_waitcnt lgkmcnt(3)
	v_mfma_f32_32x32x16_bf16 v[64:79], v[192:195], v[230:233], v[64:79]
	s_waitcnt lgkmcnt(2)
	v_mfma_f32_32x32x16_bf16 v[80:95], v[188:191], v[234:237], v[80:95]
	s_waitcnt lgkmcnt(1)
	v_mfma_f32_32x32x16_bf16 v[64:79], v[184:187], v[238:241], v[64:79]
	s_waitcnt lgkmcnt(0)
	v_mfma_f32_32x32x16_bf16 v[80:95], v[180:183], v[242:245], v[80:95]
	s_setprio 0
	v_lshl_add_u64 v[246:247], v[174:175], 0, s[48:49]
	s_mov_b32 s42, 0x20900000
	v_add_co_u32_e64 v248, s[42:43], s42, v246
	s_nop 1
	v_addc_co_u32_e64 v249, s[42:43], 0, v247, s[42:43]
	s_mov_b32 s42, 0x20901000
	v_add_co_u32_e64 v246, s[42:43], s42, v246
	s_nop 1
	v_addc_co_u32_e64 v247, s[42:43], 0, v247, s[42:43]
	global_load_dwordx4 v[154:157], v[248:249], off offset:1024
	global_load_dwordx4 v[150:153], v[248:249], off offset:2048
	global_load_dwordx4 v[142:145], v[248:249], off offset:3072
	global_load_dwordx4 v[158:161], v[246:247], off offset:-4096
	global_load_dwordx4 v[146:149], v[246:247], off
	global_load_dwordx4 v[138:141], v[246:247], off offset:1024
	global_load_dwordx4 v[134:137], v[246:247], off offset:2048
	global_load_dwordx4 v[130:133], v[246:247], off offset:3072
	v_lshlrev_b64 v[250:251], 13, v[162:163]
	v_lshl_add_u64 v[250:251], v[170:171], 0, v[250:251]
	v_add_co_u32_e64 v252, s[42:43], s58, v250
	s_nop 1
	v_addc_co_u32_e64 v253, s[42:43], 0, v251, s[42:43]
	global_load_dwordx4 v[98:101], v[250:251], off
	global_load_dwordx4 v[102:105], v[250:251], off offset:1024
	global_load_dwordx4 v[106:109], v[250:251], off offset:2048
	global_load_dwordx4 v[110:113], v[250:251], off offset:3072
	global_load_dwordx4 v[114:117], v[252:253], off
	global_load_dwordx4 v[118:121], v[252:253], off offset:1024
	global_load_dwordx4 v[122:125], v[252:253], off offset:2048
	global_load_dwordx4 v[126:129], v[252:253], off offset:3072
	s_nop 0
	v_add_f32_e32 v64, v64, v80
	v_exp_f32_e64 v80, -|v64|
	v_add_f32_e32 v65, v65, v81
	v_add_f32_e32 v66, v66, v82
	v_exp_f32_e64 v82, -|v65|
	v_add_f32_e32 v81, 1.0, v80
	v_rcp_f32_e32 v81, v81
	v_add_f32_e32 v67, v67, v83
	v_add_f32_e32 v83, 1.0, v82
	v_cmp_le_f32_e64 s[42:43], 0, v64
	v_mul_f32_e32 v80, v80, v81
	v_rcp_f32_e32 v83, v83
	v_cndmask_b32_e64 v64, v80, v81, s[42:43]
	v_add_f32_e32 v68, v68, v84
	v_cndmask_b32_e64 v84, 0, v64, s[44:45]
	v_cndmask_b32_e64 v64, v81, v80, s[42:43]
	v_exp_f32_e64 v81, -|v66|
	v_cndmask_b32_e64 v80, 1.0, v64, s[44:45]
	v_mul_f32_e32 v64, v82, v83
	v_cmp_le_f32_e64 s[42:43], 0, v65
	s_or_b64 s[44:45], s[8:9], s[50:51]
	v_add_f32_e32 v69, v69, v85
	v_cndmask_b32_e64 v65, v64, v83, s[42:43]
	v_cndmask_b32_e64 v64, v83, v64, s[42:43]
	v_cndmask_b32_e64 v82, 0, v65, s[44:45]
	v_add_f32_e32 v65, 1.0, v81
	v_cndmask_b32_e64 v83, 1.0, v64, s[44:45]
	v_exp_f32_e64 v64, -|v67|
	v_rcp_f32_e32 v65, v65
	v_cmp_le_f32_e64 s[42:43], 0, v66
	s_or_b64 s[44:45], s[10:11], s[50:51]
	v_add_f32_e32 v85, 1.0, v64
	v_mul_f32_e32 v81, v81, v65
	v_rcp_f32_e32 v85, v85
	v_cndmask_b32_e64 v66, v81, v65, s[42:43]
	v_cndmask_b32_e64 v65, v65, v81, s[42:43]
	v_cndmask_b32_e64 v81, 1.0, v65, s[44:45]
	v_exp_f32_e64 v65, -|v68|
	v_mul_f32_e32 v64, v64, v85
	v_cmp_le_f32_e64 s[42:43], 0, v67
	v_exp_f32_e64 v67, -|v69|
	v_add_f32_e32 v70, v70, v86
	v_cndmask_b32_e64 v86, 0, v66, s[44:45]
	v_cndmask_b32_e64 v66, v64, v85, s[42:43]
	s_or_b64 s[44:45], s[12:13], s[50:51]
	v_add_f32_e32 v71, v71, v87
	v_cndmask_b32_e64 v87, 0, v66, s[44:45]
	v_add_f32_e32 v66, 1.0, v65
	v_rcp_f32_e32 v66, v66
	v_cndmask_b32_e64 v64, v85, v64, s[42:43]
	v_cmp_le_f32_e64 s[42:43], 0, v68
	v_add_f32_e32 v68, 1.0, v67
	v_rcp_f32_e32 v68, v68
	v_cndmask_b32_e64 v85, 1.0, v64, s[44:45]
	v_mul_f32_e32 v64, v65, v66
	v_cndmask_b32_e64 v65, v64, v66, s[42:43]
	s_or_b64 s[44:45], s[14:15], s[50:51]
	v_add_f32_e32 v72, v72, v88
	v_cndmask_b32_e64 v88, 0, v65, s[44:45]
	v_mul_f32_e32 v65, v67, v68
	v_exp_f32_e64 v67, -|v70|
	v_cndmask_b32_e64 v64, v66, v64, s[42:43]
	v_cmp_le_f32_e64 s[42:43], 0, v69
	v_cndmask_b32_e64 v64, 1.0, v64, s[44:45]
	s_or_b64 s[44:45], s[16:17], s[50:51]
	v_cndmask_b32_e64 v66, v65, v68, s[42:43]
	v_add_f32_e32 v73, v73, v89
	v_cndmask_b32_e64 v89, 0, v66, s[44:45]
	v_add_f32_e32 v66, 1.0, v67
; __device__ __forceinline__ void attn_wave_item(const Params& p, int witem, const int tidx) {
;     ...
;     for (int r = 0; r < 16; ++r) {
;       float z = S[r];
;       float e = __builtin_amdgcn_exp2f(-fabsf(z));
;       float rr = __builtin_amdgcn_rcpf(1.f + e);
;       float sm = e * rr;
;       int kl = (r & 3) + 8 * (r >> 2) + 4 * half;
;       bool v = !diag || (kl < n);
;       bool pos = z >= 0.f;
;       be[r] = v ? (pos ? rr : sm) : 0.f;
;       om[r] = v ? (pos ? sm : rr) : 1.f;
;     }
;     float gp[4], pgp[4];
; #pragma unroll
;     for (int gi = 0; gi < 4; ++gi) {
;       gp[gi] = (om[4 * gi] * om[4 * gi + 1]) * (om[4 * gi + 2] * om[4 * gi + 3]);
;       pgp[gi] = __shfl_xor(gp[gi], 32, 64);
;     }
;     float w[16];
;     float run = R;
; #pragma unroll
;     ...
;       float a = (half == 0) ? (run * pgp[gi]) : run;
; #pragma unroll
;       for (int r = 3; r >= 0; --r) {
;         int ri = 4 * gi + r;
;         w[ri] = be[ri] * a;
;         a *= om[ri];
;       }
;       run *= gp[gi] * pgp[gi];
;     }
;     R = run;
;     __builtin_amdgcn_sched_barrier(0);
;     bf16x8 pf[2];
; #pragma unroll
;     for (int m = 0; m < 2; ++m) {
;       u32x4 t;
;       t.x = pack2(w[8 * m + 0], w[8 * m + 1]);
;       t.y = pack2(w[8 * m + 2], w[8 * m + 3]);
;       t.z = pack2(w[8 * m + 4], w[8 * m + 5]);
;       t.w = pack2(w[8 * m + 6], w[8 * m + 7]);
;       pf[m] = as_bf16x8(t);
;     }
; #pragma unroll
;     for (int dt = 0; dt < 4; ++dt)
; #pragma unroll
;       for (int m = 0; m < 2; ++m) O[dt] = __builtin_amdgcn_mfma_f32_32x32x16_bf16(as_bf16x8(vf[dt * 2 + m]), pf[m], O[dt], 0, 0, 0);
;     if (__all(R < 1.17549435e-38f)) break;
;     __builtin_amdgcn_sched_barrier(0);
; #pragma unroll
;     for (int i = 0; i < 8; ++i) kf[i] = kn[i];
	v_cndmask_b32_e64 v65, v68, v65, s[42:43]
	v_rcp_f32_e32 v69, v66
	v_cndmask_b32_e64 v66, 1.0, v65, s[44:45]
	v_exp_f32_e64 v65, -|v71|
	v_cmp_le_f32_e64 s[42:43], 0, v70
	v_mul_f32_e32 v67, v67, v69
	s_or_b64 s[44:45], s[18:19], s[50:51]
	v_add_f32_e32 v70, 1.0, v65
	v_rcp_f32_e32 v70, v70
	v_cndmask_b32_e64 v68, v67, v69, s[42:43]
	v_cndmask_b32_e64 v67, v69, v67, s[42:43]
	v_cndmask_b32_e64 v176, 1.0, v67, s[44:45]
	v_exp_f32_e64 v67, -|v72|
	v_mul_f32_e32 v65, v65, v70
	v_cmp_le_f32_e64 s[42:43], 0, v71
	v_add_f32_e32 v74, v74, v90
	v_cndmask_b32_e64 v90, 0, v68, s[44:45]
	v_cndmask_b32_e64 v68, v65, v70, s[42:43]
	s_or_b64 s[44:45], s[20:21], s[50:51]
	v_cndmask_b32_e64 v71, 0, v68, s[44:45]
	v_add_f32_e32 v68, 1.0, v67
	v_cndmask_b32_e64 v65, v70, v65, s[42:43]
	v_rcp_f32_e32 v69, v68
	v_cndmask_b32_e64 v68, 1.0, v65, s[44:45]
	v_exp_f32_e64 v65, -|v73|
	v_cmp_le_f32_e64 s[42:43], 0, v72
	v_mul_f32_e32 v67, v67, v69
	s_or_b64 s[44:45], s[22:23], s[50:51]
	v_add_f32_e32 v72, 1.0, v65
	v_rcp_f32_e32 v72, v72
	v_cndmask_b32_e64 v70, v67, v69, s[42:43]
	v_cndmask_b32_e64 v67, v69, v67, s[42:43]
	v_cmp_le_f32_e64 s[42:43], 0, v73
	v_mul_f32_e32 v65, v65, v72
	v_add_f32_e32 v75, v75, v91
	v_cndmask_b32_e64 v91, 0, v70, s[44:45]
	v_cndmask_b32_e64 v67, 1.0, v67, s[44:45]
	v_exp_f32_e64 v69, -|v74|
	v_cndmask_b32_e64 v70, v65, v72, s[42:43]
	s_or_b64 s[44:45], s[24:25], s[50:51]
	v_cndmask_b32_e64 v65, v72, v65, s[42:43]
	v_add_f32_e32 v77, v77, v93
	v_cndmask_b32_e64 v93, 1.0, v65, s[44:45]
	v_exp_f32_e64 v65, -|v75|
	v_add_f32_e32 v76, v76, v92
	v_cndmask_b32_e64 v92, 0, v70, s[44:45]
	v_add_f32_e32 v70, 1.0, v69
	v_rcp_f32_e32 v70, v70
	v_add_f32_e32 v73, 1.0, v65
	v_rcp_f32_e32 v73, v73
	v_cmp_le_f32_e64 s[42:43], 0, v74
	v_mul_f32_e32 v69, v69, v70
	s_or_b64 s[44:45], s[26:27], s[50:51]
	v_cndmask_b32_e64 v72, v69, v70, s[42:43]
	v_cndmask_b32_e64 v69, v70, v69, s[42:43]
	v_mul_f32_e32 v65, v65, v73
	v_cmp_le_f32_e64 s[42:43], 0, v75
	v_add_f32_e32 v78, v78, v94
	v_add_f32_e32 v79, v79, v95
	v_cndmask_b32_e64 v94, 0, v72, s[44:45]
	v_cndmask_b32_e64 v95, 1.0, v69, s[44:45]
	v_exp_f32_e64 v69, -|v76|
	v_cndmask_b32_e64 v70, v65, v73, s[42:43]
	s_or_b64 s[44:45], s[28:29], s[50:51]
	v_cndmask_b32_e64 v65, v73, v65, s[42:43]
	v_cndmask_b32_e64 v179, 1.0, v65, s[44:45]
	v_exp_f32_e64 v65, -|v77|
	v_cndmask_b32_e64 v162, 0, v70, s[44:45]
	v_add_f32_e32 v70, 1.0, v69
	v_rcp_f32_e32 v70, v70
	v_add_f32_e32 v73, 1.0, v65
	v_rcp_f32_e32 v73, v73
	v_cmp_le_f32_e64 s[42:43], 0, v76
	v_mul_f32_e32 v69, v69, v70
	s_or_b64 s[44:45], s[30:31], s[50:51]
	v_cndmask_b32_e64 v72, v69, v70, s[42:43]
	v_cndmask_b32_e64 v69, v70, v69, s[42:43]
	v_mul_f32_e32 v65, v65, v73
	v_cmp_le_f32_e64 s[42:43], 0, v77
	v_cndmask_b32_e64 v74, 0, v72, s[44:45]
	v_cndmask_b32_e64 v69, 1.0, v69, s[44:45]
	v_exp_f32_e64 v70, -|v78|
	v_cndmask_b32_e64 v72, v65, v73, s[42:43]
	s_or_b64 s[44:45], s[34:35], s[50:51]
	v_cndmask_b32_e64 v65, v73, v65, s[42:43]
	v_cndmask_b32_e64 v73, 1.0, v65, s[44:45]
	v_exp_f32_e64 v65, -|v79|
	v_cndmask_b32_e64 v75, 0, v72, s[44:45]
	v_add_f32_e32 v72, 1.0, v70
	v_rcp_f32_e32 v72, v72
	v_add_f32_e32 v77, 1.0, v65
	v_rcp_f32_e32 v77, v77
	v_cmp_le_f32_e64 s[42:43], 0, v78
	v_mul_f32_e32 v70, v70, v72
	s_or_b64 s[44:45], s[36:37], s[50:51]
	v_cndmask_b32_e64 v76, v70, v72, s[42:43]
	v_cndmask_b32_e64 v70, v72, v70, s[42:43]
	v_mul_f32_e32 v65, v65, v77
	v_cmp_le_f32_e64 s[42:43], 0, v79
	v_cndmask_b32_e64 v76, 0, v76, s[44:45]
	v_cndmask_b32_e64 v78, 1.0, v70, s[44:45]
	v_cndmask_b32_e64 v70, v65, v77, s[42:43]
	s_or_b64 s[44:45], s[38:39], s[50:51]
	v_cndmask_b32_e64 v65, v77, v65, s[42:43]
	v_cndmask_b32_e64 v77, 1.0, v65, s[44:45]
	v_mul_f32_e32 v65, v69, v73
	v_mul_f32_e32 v69, v78, v77
	v_mul_f32_e32 v69, v65, v69
	v_cndmask_b32_e64 v79, 0, v70, s[44:45]
	v_mul_f32_e32 v70, v80, v83
	ds_bpermute_b32 v80, v178, v69
	v_mul_f32_e32 v65, v67, v93
	v_mul_f32_e32 v67, v95, v179
	v_mul_f32_e32 v65, v65, v67
	ds_bpermute_b32 v67, v178, v65
	s_waitcnt lgkmcnt(1)
	v_mul_f32_e32 v180, v177, v80
	v_cndmask_b32_e32 v180, v177, v180, vcc
	v_mul_f32_e32 v77, v180, v77
	v_mul_f32_e32 v76, v76, v77
	v_mul_f32_e32 v77, v78, v77
	v_mul_f32_e32 v73, v73, v77
	v_mul_f32_e32 v69, v69, v80
	v_mul_f32_e32 v78, v75, v77
	v_mul_f32_e32 v77, v74, v73
	v_pk_mul_f32 v[74:75], v[176:177], v[68:69]
	s_waitcnt lgkmcnt(0)
	v_pk_mul_f32 v[64:65], v[64:65], v[66:67]
	v_mul_f32_e32 v67, v75, v67
	v_pk_mul_f32 v[64:65], v[64:65], v[74:75]
	ds_bpermute_b32 v73, v178, v64
	v_cndmask_b32_e32 v67, v75, v67, vcc
	v_mul_f32_e32 v74, v162, v67
	v_mul_f32_e32 v67, v179, v67
	v_mul_f32_e32 v75, v94, v67
	v_mul_f32_e32 v67, v95, v67
	v_mul_f32_e32 v80, v92, v67
	v_mul_f32_e32 v67, v93, v67
	v_mul_f32_e32 v91, v91, v67
	s_waitcnt lgkmcnt(0)
	v_mul_f32_e32 v67, v65, v73
	v_cndmask_b32_e32 v67, v65, v67, vcc
	v_mul_f32_e32 v72, v81, v85
	v_mul_f32_e32 v92, v71, v67
	v_mov_b32_e32 v71, v64
	v_mul_f32_e32 v67, v68, v67
	v_pk_mul_f32 v[68:69], v[70:71], v[72:73]
	ds_bpermute_b32 v64, v178, v68
	v_mul_f32_e32 v90, v90, v67
	v_mul_f32_e32 v67, v176, v67
	v_mul_f32_e32 v70, v89, v67
	v_mul_f32_e32 v66, v66, v67
	s_waitcnt lgkmcnt(0)
	v_pk_mul_f32 v[72:73], v[68:69], v[64:65]
	v_mul_f32_e32 v79, v180, v79
	v_mul_f32_e32 v64, v73, v64
	v_cndmask_b32_e32 v64, v73, v64, vcc
	v_mul_f32_e32 v65, v87, v64
	v_mul_f32_e32 v64, v85, v64
	v_mul_f32_e32 v67, v86, v64
	v_mul_f32_e32 v64, v81, v64
	v_mul_f32_e32 v68, v82, v64
	v_mul_f32_e32 v64, v83, v64
	v_mul_f32_e32 v66, v88, v66
	v_mul_f32_e32 v64, v84, v64
	v_cvt_pk_bf16_f32 v64, v64, v68
	v_cvt_pk_bf16_f32 v65, v67, v65
	v_cvt_pk_bf16_f32 v66, v66, v70
	v_cvt_pk_bf16_f32 v67, v90, v92
	v_cvt_pk_bf16_f32 v68, v91, v80
	v_cvt_pk_bf16_f32 v69, v75, v74
	v_cvt_pk_bf16_f32 v70, v77, v78
	v_cvt_pk_bf16_f32 v71, v76, v79
	v_mul_f32_e32 v177, v72, v73
	s_waitcnt vmcnt(12)
	s_setprio 1
	v_mfma_f32_32x32x16_bf16 v[48:63], v[158:161], v[64:67], v[48:63]
	v_cmp_gt_f32_e64 s[42:43], s1, v177
	s_or_b64 s[92:93], s[92:93], exec
	s_mov_b64 s[44:45], -1
	s_cmp_lg_u64 s[42:43], exec
	v_mfma_f32_32x32x16_bf16 v[32:47], v[150:153], v[64:67], v[32:47]
	s_waitcnt vmcnt(11)
	v_mfma_f32_32x32x16_bf16 v[16:31], v[146:149], v[64:67], v[16:31]
	s_waitcnt vmcnt(9)
	v_mfma_f32_32x32x16_bf16 v[0:15], v[134:137], v[64:67], v[0:15]
	v_mfma_f32_32x32x16_bf16 v[48:63], v[154:157], v[68:71], v[48:63]
	v_mfma_f32_32x32x16_bf16 v[32:47], v[142:145], v[68:71], v[32:47]
	v_mfma_f32_32x32x16_bf16 v[16:31], v[138:141], v[68:71], v[16:31]
	s_waitcnt vmcnt(8)
	v_mfma_f32_32x32x16_bf16 v[0:15], v[130:133], v[68:71], v[0:15]
	s_setprio 0
	s_cbranch_scc1 .LBB0_117
	s_branch .LBB0_118
